# v62 + MLA attention unit prologue: first K/V chunk loads issued before the Q loads and rope processing (free VGPRs, moved into place), one exposed round trip less per unit
# speedup vs baseline: 1.0033x; 1.0033x over previous
.LBB0_652:
	v_add_u32_e32 v156, s40, v139
	s_mul_i32 s40, s55, 0x60
	v_mov_b64_e32 v[2:3], s[14:15]
	s_ashr_i32 s41, s40, 31
	v_mad_i64_i32 v[2:3], s[12:13], v156, s19, v[2:3]
	v_lshl_add_u64 v[2:3], s[40:41], 1, v[2:3]
	v_lshlrev_b32_e32 v0, 1, v138
	v_lshl_add_u64 v[2:3], v[2:3], 0, v[0:1]
	s_lshl_b64 s[56:57], s[40:41], 1
	s_add_u32 s60, s48, s56
	s_addc_u32 s61, s49, s57
	v_lshlrev_b64 v[246:247], 1, v[146:147]
	v_lshlrev_b64 v[248:249], 1, v[148:149]
	v_lshl_add_u64 v[246:247], v[140:141], 1, v[246:247]
	v_lshl_add_u64 v[248:249], v[142:143], 1, v[248:249]
	v_lshl_add_u64 v[246:247], s[60:61], 0, v[246:247]
	v_lshl_add_u64 v[248:249], s[60:61], 0, v[248:249]
	s_lshl_b32 s56, s55, 6
	s_ashr_i32 s57, s56, 31
	s_lshl_b64 s[56:57], s[56:57], 1
	v_lshl_add_u64 v[250:251], s[52:53], 0, v[150:151]
	v_lshl_add_u64 v[250:251], v[250:251], 0, s[56:57]
	v_lshl_add_u64 v[250:251], v[250:251], 0, v[152:153]
	global_load_dwordx4 v[234:237], v[246:247], off
	global_load_dwordx4 v[238:241], v[248:249], off
	global_load_dwordx4 v[242:245], v[250:251], off
	global_load_dwordx4 v[18:21], v[2:3], off
	global_load_dwordx4 v[22:25], v[2:3], off offset:64
	global_load_dwordx4 v[44:47], v[2:3], off offset:128
	s_nop 0
	global_load_dwordx4 v[2:5], v[144:145], off offset:16
	global_load_dwordx4 v[10:13], v[144:145], off
	global_load_dwordx4 v[48:51], v[144:145], off offset:272
	global_load_dwordx4 v[52:55], v[144:145], off offset:256
	global_load_dwordx4 v[6:9], v[144:145], off offset:144
	global_load_dwordx4 v[14:17], v[144:145], off offset:128
	s_waitcnt vmcnt(28)
	v_and_b32_e32 v27, 64, v232
	v_xor_b32_e32 v26, 16, v232
	s_waitcnt vmcnt(24)
	v_add_u32_e32 v43, 64, v27
	v_cmp_lt_i32_e32 vcc, v26, v43
	v_ashrrev_i32_e32 v157, 31, v156
	s_waitcnt vmcnt(8)
	v_and_b32_e32 v41, 0xffff0000, v18
	v_cndmask_b32_e32 v26, v232, v26, vcc
	v_lshlrev_b32_e32 v155, 2, v26
	v_lshlrev_b32_e32 v42, 16, v18
	v_mul_f32_e32 v26, v41, v41
	v_lshlrev_b32_e32 v40, 16, v19
	v_fmac_f32_e32 v26, v42, v42
	v_and_b32_e32 v39, 0xffff0000, v19
	v_fmac_f32_e32 v26, v40, v40
	v_lshlrev_b32_e32 v38, 16, v20
	v_fmac_f32_e32 v26, v39, v39
	v_and_b32_e32 v37, 0xffff0000, v20
	v_fmac_f32_e32 v26, v38, v38
	v_lshlrev_b32_e32 v36, 16, v21
	v_fmac_f32_e32 v26, v37, v37
	v_and_b32_e32 v35, 0xffff0000, v21
	v_fmac_f32_e32 v26, v36, v36
	s_waitcnt vmcnt(7)
	v_lshlrev_b32_e32 v34, 16, v22
	v_fmac_f32_e32 v26, v35, v35
	v_and_b32_e32 v33, 0xffff0000, v22
	v_fmac_f32_e32 v26, v34, v34
	v_lshlrev_b32_e32 v32, 16, v23
	v_fmac_f32_e32 v26, v33, v33
	v_and_b32_e32 v31, 0xffff0000, v23
	v_fmac_f32_e32 v26, v32, v32
	v_lshlrev_b32_e32 v30, 16, v24
	v_fmac_f32_e32 v26, v31, v31
	v_and_b32_e32 v29, 0xffff0000, v24
	v_fmac_f32_e32 v26, v30, v30
	v_lshlrev_b32_e32 v28, 16, v25
	v_fmac_f32_e32 v26, v29, v29
	v_and_b32_e32 v27, 0xffff0000, v25
	s_waitcnt vmcnt(6)
	v_and_b32_e32 v25, 0xffff0000, v44
	v_lshlrev_b32_e32 v24, 16, v44
	v_fmac_f32_e32 v26, v28, v28
	v_pk_mul_f32 v[58:59], v[24:25], v[24:25]
	v_fmac_f32_e32 v26, v27, v27
	v_and_b32_e32 v23, 0xffff0000, v45
	v_lshlrev_b32_e32 v22, 16, v45
	v_add_f32_e32 v26, v58, v26
	v_pk_mul_f32 v[56:57], v[22:23], v[22:23]
	v_add_f32_e32 v26, v59, v26
	v_and_b32_e32 v21, 0xffff0000, v46
	v_lshlrev_b32_e32 v20, 16, v46
	v_add_f32_e32 v26, v56, v26
	v_and_b32_e32 v19, 0xffff0000, v47
	v_lshlrev_b32_e32 v18, 16, v47
	v_pk_mul_f32 v[46:47], v[20:21], v[20:21]
	v_add_f32_e32 v26, v57, v26
	v_add_f32_e32 v26, v46, v26
	v_pk_mul_f32 v[44:45], v[18:19], v[18:19]
	v_add_f32_e32 v26, v47, v26
	v_add_f32_e32 v26, v44, v26
	v_add_f32_e32 v26, v45, v26
	ds_bpermute_b32 v44, v155, v26
	v_xor_b32_e32 v45, 32, v232
	v_cmp_lt_i32_e32 vcc, v45, v43
	s_waitcnt lgkmcnt(0)
	v_add_f32_e32 v26, v26, v44
	v_cndmask_b32_e32 v43, v232, v45, vcc
	v_lshlrev_b32_e32 v176, 2, v43
	ds_bpermute_b32 v43, v176, v26
	v_cndmask_b32_e64 v44, 0, 1, s[70:71]
	v_cmp_ne_u32_e64 s[12:13], 1, v44
	s_andn2_b64 vcc, exec, s[70:71]
	s_waitcnt lgkmcnt(0)
	v_add_f32_e32 v26, v26, v43
	v_fmamk_f32 v26, v26, 0x3c2aaaab, v227
	v_rsq_f32_e32 v26, v26
	s_nop 0
	v_pk_mul_f32 v[24:25], v[26:27], v[24:25] op_sel_hi:[0,1]
	v_pk_mul_f32 v[22:23], v[26:27], v[22:23] op_sel_hi:[0,1]
	v_pk_mul_f32 v[20:21], v[26:27], v[20:21] op_sel_hi:[0,1]
	v_pk_mul_f32 v[18:19], v[26:27], v[18:19] op_sel_hi:[0,1]
	s_waitcnt vmcnt(2)
	v_pk_mul_f32 v[24:25], v[52:53], v[24:25]
	v_pk_mul_f32 v[22:23], v[54:55], v[22:23]
	v_pk_mul_f32 v[20:21], v[48:49], v[20:21]
	v_pk_mul_f32 v[18:19], v[50:51], v[18:19]
	s_cbranch_vccnz .LBB0_654
	v_and_b32_e32 v43, 63, v156
	v_bfe_u32 v44, v156, 6, 4
	v_cndmask_b32_e64 v43, v43, v44, s[8:9]
	v_lshlrev_b32_e32 v43, 6, v43
	global_load_dwordx4 v[44:47], v43, s[26:27] offset:48
	global_load_dwordx4 v[48:51], v43, s[26:27] offset:32
	global_load_dwordx4 v[52:55], v43, s[26:27] offset:16
	global_load_dwordx4 v[56:59], v43, s[26:27]
	ds_bpermute_b32 v60, v155, v24
	ds_bpermute_b32 v61, v155, v25
	s_waitcnt vmcnt(0)
	v_mov_b32_e32 v63, v58
	v_mov_b32_e32 v58, v57
	v_mov_b32_e32 v62, v56
	s_waitcnt lgkmcnt(0)
	v_pk_mul_f32 v[56:57], v[58:59], v[60:61]
	v_mov_b32_e32 v59, v54
	v_cndmask_b32_e64 v57, v57, -v57, s[10:11]
	v_cndmask_b32_e64 v56, v56, -v56, s[10:11]
	v_pk_fma_f32 v[24:25], v[24:25], v[62:63], v[56:57]
	ds_bpermute_b32 v56, v155, v22
	ds_bpermute_b32 v57, v155, v23
	v_mov_b32_e32 v54, v53
	v_mov_b32_e32 v58, v52
	s_waitcnt lgkmcnt(0)
	v_pk_mul_f32 v[52:53], v[54:55], v[56:57]
	s_nop 0
	v_cndmask_b32_e64 v53, v53, -v53, s[10:11]
	v_cndmask_b32_e64 v52, v52, -v52, s[10:11]
	v_pk_fma_f32 v[22:23], v[22:23], v[58:59], v[52:53]
	ds_bpermute_b32 v52, v155, v20
	ds_bpermute_b32 v53, v155, v21
	v_mov_b32_e32 v55, v50
	v_mov_b32_e32 v50, v49
	v_mov_b32_e32 v54, v48
	s_waitcnt lgkmcnt(0)
	v_pk_mul_f32 v[48:49], v[50:51], v[52:53]
	s_nop 0
	v_cndmask_b32_e64 v49, v49, -v49, s[10:11]
	v_cndmask_b32_e64 v48, v48, -v48, s[10:11]
	v_pk_fma_f32 v[20:21], v[20:21], v[54:55], v[48:49]
	ds_bpermute_b32 v48, v155, v18
	ds_bpermute_b32 v49, v155, v19
	v_mov_b32_e32 v51, v46
	v_mov_b32_e32 v46, v45
	v_mov_b32_e32 v50, v44
	s_waitcnt lgkmcnt(0)
	v_pk_mul_f32 v[44:45], v[46:47], v[48:49]
	s_nop 0
	v_cndmask_b32_e64 v45, v45, -v45, s[10:11]
	v_cndmask_b32_e64 v44, v44, -v44, s[10:11]
	v_pk_fma_f32 v[18:19], v[18:19], v[50:51], v[44:45]

.LBB0_656:
	s_lshl_b32 s12, s55, 6
	s_lshl_b64 s[56:57], s[40:41], 1
	v_mul_f32_e32 v41, v0, v41
	s_add_u32 s40, s48, s56
	v_mul_f32_e32 v53, v0, v53
	v_mul_f32_e32 v52, v0, v52
	s_waitcnt vmcnt(1)
	v_mul_f32_e32 v41, v14, v41
	v_mul_f32_e32 v14, v0, v40
	s_addc_u32 s41, s49, s57
	s_ashr_i32 s13, s12, 31
	v_mul_f32_e32 v26, v26, v53
	v_mul_f32_e32 v27, v27, v52
	v_mul_f32_e32 v40, v15, v14
	v_mul_f32_e32 v14, v0, v39
	s_lshl_b64 s[12:13], s[12:13], 1
	v_mul_f32_e32 v45, v0, v45
	v_mul_f32_e32 v44, v0, v44
	v_mul_f32_e32 v43, v0, v43
	v_mul_f32_e32 v42, v0, v42
	v_mul_f32_e32 v39, v16, v14
	v_cvt_pk_bf16_f32 v14, v26, v27
	v_lshl_add_u64 v[26:27], s[52:53], 0, v[150:151]
	s_add_u32 s60, s40, 0x30000
	v_mul_f32_e32 v51, v0, v51
	v_mul_f32_e32 v50, v0, v50
	v_mul_f32_e32 v49, v0, v49
	v_mul_f32_e32 v48, v0, v48
	v_mul_f32_e32 v47, v0, v47
	v_mul_f32_e32 v46, v0, v46
	s_waitcnt vmcnt(0)
	v_mul_f32_e32 v18, v18, v45
	v_mul_f32_e32 v19, v19, v44
	v_mul_f32_e32 v20, v20, v43
	v_mul_f32_e32 v21, v21, v42
	v_mul_f32_e32 v0, v0, v38
	v_lshl_add_u64 v[26:27], v[26:27], 0, s[12:13]
	v_lshlrev_b64 v[62:63], 1, v[146:147]
	v_lshlrev_b64 v[66:67], 1, v[148:149]
	s_addc_u32 s61, s41, 0
	v_mul_f32_e32 v28, v28, v51
	v_mul_f32_e32 v29, v29, v50
	v_mul_f32_e32 v22, v22, v49
	v_mul_f32_e32 v23, v23, v48
	v_mul_f32_e32 v24, v24, v47
	v_mul_f32_e32 v25, v25, v46
	v_mul_f32_e32 v0, v17, v0
	v_cvt_pk_bf16_f32 v15, v28, v29
	v_cvt_pk_bf16_f32 v16, v22, v23
	v_cvt_pk_bf16_f32 v17, v24, v25
	v_cvt_pk_bf16_f32 v18, v18, v19
	v_cvt_pk_bf16_f32 v19, v20, v21
	v_cvt_pk_bf16_f32 v20, v41, v40
	v_cvt_pk_bf16_f32 v21, v39, v0
	v_lshl_add_u64 v[70:71], v[26:27], 0, v[152:153]
	v_lshl_add_u64 v[38:39], s[60:61], 0, v[62:63]
	v_lshl_add_u64 v[40:41], s[60:61], 0, v[66:67]
	s_mov_b32 s4, 0x20000
	s_add_u32 s60, s40, 0x60000
	v_add_co_u32_e32 v46, vcc, s4, v70
	s_addc_u32 s61, s41, 0
	v_lshl_add_u64 v[26:27], s[40:41], 0, v[62:63]
	v_lshl_add_u64 v[28:29], s[40:41], 0, v[66:67]
	v_addc_co_u32_e32 v47, vcc, 0, v71, vcc
	s_mov_b32 s4, 0x40000
	s_add_u32 s40, s40, 0x90000
	v_lshlrev_b64 v[64:65], 1, v[140:141]
	v_lshlrev_b64 v[68:69], 1, v[142:143]
	v_add_co_u32_e32 v58, vcc, s4, v70
	s_addc_u32 s41, s41, 0
	v_cvt_pk_bf16_f32 v22, v36, v37
	v_cvt_pk_bf16_f32 v23, v34, v35
	v_cvt_pk_bf16_f32 v24, v32, v33
	v_cvt_pk_bf16_f32 v25, v30, v31
	v_lshl_add_u64 v[26:27], v[26:27], 0, v[64:65]
	v_lshl_add_u64 v[30:31], v[28:29], 0, v[68:69]
	v_lshl_add_u64 v[50:51], s[60:61], 0, v[62:63]
	v_addc_co_u32_e32 v59, vcc, 0, v71, vcc
	v_lshl_add_u64 v[62:63], s[40:41], 0, v[62:63]
	s_mov_b32 s4, 0x60000
	v_mov_b64_e32 v[26:27], v[234:235]
	v_mov_b64_e32 v[28:29], v[236:237]
	s_nop 0
	v_mov_b64_e32 v[30:31], v[238:239]
	v_mov_b64_e32 v[32:33], v[240:241]
	s_nop 0
	v_mov_b64_e32 v[34:35], v[242:243]
	v_mov_b64_e32 v[36:37], v[244:245]
	v_lshl_add_u64 v[38:39], v[38:39], 0, v[64:65]
	v_lshl_add_u64 v[50:51], v[50:51], 0, v[64:65]
	v_lshl_add_u64 v[52:53], s[60:61], 0, v[66:67]
	v_lshl_add_u64 v[62:63], v[62:63], 0, v[64:65]
	v_lshl_add_u64 v[64:65], s[40:41], 0, v[66:67]
	v_add_co_u32_e32 v70, vcc, s4, v70
	v_lshl_add_u64 v[42:43], v[40:41], 0, v[68:69]
	v_lshl_add_u64 v[54:55], v[52:53], 0, v[68:69]
	v_lshl_add_u64 v[66:67], v[64:65], 0, v[68:69]
	v_addc_co_u32_e32 v71, vcc, 0, v71, vcc
	global_load_dwordx4 v[38:41], v[38:39], off
	s_nop 0
	global_load_dwordx4 v[42:45], v[42:43], off
	s_add_i32 s55, s54, -1
	global_load_dwordx4 v[46:49], v[46:47], off
	s_nop 0
	global_load_dwordx4 v[50:53], v[50:51], off
	s_nop 0
	global_load_dwordx4 v[54:57], v[54:55], off
	s_cmp_eq_u32 s55, 3
	global_load_dwordx4 v[58:61], v[58:59], off
	s_nop 0
	global_load_dwordx4 v[62:65], v[62:63], off
	s_nop 0
	global_load_dwordx4 v[66:69], v[66:67], off
	s_cselect_b64 s[40:41], -1, 0
	global_load_dwordx4 v[70:73], v[70:71], off
	s_and_b64 s[60:61], s[40:41], exec
	s_cselect_b32 s45, s53, s45
	s_cselect_b32 s44, s52, s44
	v_lshl_add_u64 v[74:75], s[44:45], 0, v[150:151]
	s_cselect_b32 s42, s48, s42
	v_lshl_add_u64 v[74:75], v[74:75], 0, s[12:13]
	v_mov_b32_e32 v76, v1
	v_mov_b32_e32 v77, v1
	s_cselect_b32 s4, s49, s43
	s_add_u32 s42, s42, s56
	v_lshl_add_u64 v[162:163], v[74:75], 0, v[152:153]
	v_mov_b32_e32 v179, v178
	v_mov_b32_e32 v0, v1
	v_mov_b32_e32 v74, v1
	v_mov_b32_e32 v75, v1
	v_mov_b64_e32 v[80:81], v[76:77]
	v_mov_b64_e32 v[84:85], v[76:77]
	v_mov_b64_e32 v[88:89], v[76:77]
	v_mov_b64_e32 v[92:93], v[76:77]
	v_mov_b64_e32 v[96:97], v[76:77]
	v_mov_b64_e32 v[100:101], v[76:77]
	v_mov_b64_e32 v[104:105], v[76:77]
	s_addc_u32 s43, s4, s57
	s_mov_b32 s44, 7
	v_mov_b64_e32 v[78:79], v[74:75]
	v_mov_b64_e32 v[82:83], v[74:75]
	v_mov_b64_e32 v[86:87], v[74:75]
	v_mov_b64_e32 v[90:91], v[74:75]
	v_mov_b64_e32 v[94:95], v[74:75]
	v_mov_b64_e32 v[98:99], v[74:75]
	v_mov_b64_e32 v[102:103], v[74:75]
	v_mov_b64_e32 v[160:161], v[0:1]
	v_mov_b64_e32 v[166:167], v[178:179]
	s_branch .LBB0_658
